# CMP phase: first-GEMM operand loads and c1 partial-sum loads batched under counted waits (were one vmcnt(0) per MFMA)
# speedup vs baseline: 1.0322x; 1.0040x over previous
; #define MFMA(a, b, c) __builtin_amdgcn_mfma_f32_32x32x16_bf16((a), (b), (c), 0, 0, 0)
; DI void phase_cmp(const Params& p, int l, char* smem) {
;     ...
;     for (int ks = kh * 64; ks < kh * 64 + 64; ++ks) {
;       const bf16x8 a = *(const bf16x8*)(ap + (size_t)(ks >> 2) * QKW + (ks & 3) * 16);
;       const bf16x8 bb = *(const bf16x8*)(bp + ks * 16);
;       acc = MFMA(a, bb, acc);
;     }
;     if (kh == 1) {
; #pragma unroll
;       for (int i = 0; i < 16; ++i) part[i * 256 + (tid & 255)] = acc[i];
.LBB0_503:
	s_waitcnt vmcnt(4)
	v_add_u32_e32 v48, s13, v21
	v_ashrrev_i32_e32 v38, 2, v48
	v_mad_i64_i32 v[50:51], s[20:21], v38, s91, v[30:31]
	v_add_u32_e32 v39, 1, v38
	v_mad_i64_i32 v[52:53], s[20:21], v39, s91, v[30:31]
	v_add_u32_e32 v39, 2, v38
	v_mad_i64_i32 v[54:55], s[20:21], v39, s91, v[30:31]
	v_add_u32_e32 v39, 3, v38
	v_mad_i64_i32 v[56:57], s[20:21], v39, s91, v[30:31]
	global_load_dwordx4 v[60:63], v[50:51], off
	global_load_dwordx4 v[124:127], v[28:29], off offset:-256
	global_load_dwordx4 v[64:67], v[50:51], off offset:32
	global_load_dwordx4 v[128:131], v[28:29], off offset:-224
	global_load_dwordx4 v[68:71], v[50:51], off offset:64
	global_load_dwordx4 v[132:135], v[28:29], off offset:-192
	global_load_dwordx4 v[72:75], v[50:51], off offset:96
	global_load_dwordx4 v[136:139], v[28:29], off offset:-160
	global_load_dwordx4 v[76:79], v[52:53], off
	global_load_dwordx4 v[140:143], v[28:29], off offset:-128
	global_load_dwordx4 v[80:83], v[52:53], off offset:32
	global_load_dwordx4 v[144:147], v[28:29], off offset:-96
	global_load_dwordx4 v[84:87], v[52:53], off offset:64
	global_load_dwordx4 v[148:151], v[28:29], off offset:-64
	global_load_dwordx4 v[88:91], v[52:53], off offset:96
	global_load_dwordx4 v[156:159], v[28:29], off offset:-32
	global_load_dwordx4 v[92:95], v[54:55], off
	global_load_dwordx4 v[160:163], v[28:29], off
	global_load_dwordx4 v[96:99], v[54:55], off offset:32
	global_load_dwordx4 v[164:167], v[28:29], off offset:32
	global_load_dwordx4 v[100:103], v[54:55], off offset:64
	global_load_dwordx4 v[168:171], v[28:29], off offset:64
	global_load_dwordx4 v[104:107], v[54:55], off offset:96
	global_load_dwordx4 v[172:175], v[28:29], off offset:96
	global_load_dwordx4 v[108:111], v[56:57], off
	global_load_dwordx4 v[176:179], v[28:29], off offset:128
	global_load_dwordx4 v[112:115], v[56:57], off offset:32
	global_load_dwordx4 v[180:183], v[28:29], off offset:160
	global_load_dwordx4 v[116:119], v[56:57], off offset:64
	global_load_dwordx4 v[184:187], v[28:29], off offset:192
	global_load_dwordx4 v[120:123], v[56:57], off offset:96
	global_load_dwordx4 v[188:191], v[28:29], off offset:224
	v_lshl_add_u64 v[28:29], v[28:29], 0, s[22:23]
	s_waitcnt vmcnt(30)
	v_mfma_f32_32x32x16_bf16 v[2:17], v[60:63], v[124:127], v[2:17]
	s_waitcnt vmcnt(28)
	v_mfma_f32_32x32x16_bf16 v[2:17], v[64:67], v[128:131], v[2:17]
	s_waitcnt vmcnt(26)
	v_mfma_f32_32x32x16_bf16 v[2:17], v[68:71], v[132:135], v[2:17]
	s_waitcnt vmcnt(24)
	v_mfma_f32_32x32x16_bf16 v[2:17], v[72:75], v[136:139], v[2:17]
	s_waitcnt vmcnt(22)
	v_mfma_f32_32x32x16_bf16 v[2:17], v[76:79], v[140:143], v[2:17]
	s_waitcnt vmcnt(20)
	v_mfma_f32_32x32x16_bf16 v[2:17], v[80:83], v[144:147], v[2:17]
	s_waitcnt vmcnt(18)
	v_mfma_f32_32x32x16_bf16 v[2:17], v[84:87], v[148:151], v[2:17]
	s_waitcnt vmcnt(16)
	v_mfma_f32_32x32x16_bf16 v[2:17], v[88:91], v[156:159], v[2:17]
	s_waitcnt vmcnt(14)
	v_mfma_f32_32x32x16_bf16 v[2:17], v[92:95], v[160:163], v[2:17]
	s_waitcnt vmcnt(12)
	v_mfma_f32_32x32x16_bf16 v[2:17], v[96:99], v[164:167], v[2:17]
	s_waitcnt vmcnt(10)
	v_mfma_f32_32x32x16_bf16 v[2:17], v[100:103], v[168:171], v[2:17]
	s_waitcnt vmcnt(8)
	v_mfma_f32_32x32x16_bf16 v[2:17], v[104:107], v[172:175], v[2:17]
	s_waitcnt vmcnt(6)
	v_mfma_f32_32x32x16_bf16 v[2:17], v[108:111], v[176:179], v[2:17]
	s_waitcnt vmcnt(4)
	v_mfma_f32_32x32x16_bf16 v[2:17], v[112:115], v[180:183], v[2:17]
	s_waitcnt vmcnt(2)
	v_mfma_f32_32x32x16_bf16 v[2:17], v[116:119], v[184:187], v[2:17]
	s_waitcnt vmcnt(0)
	v_mfma_f32_32x32x16_bf16 v[2:17], v[120:123], v[188:191], v[2:17]
	s_add_i32 s13, s13, 16
	s_cmp_eq_u32 s13, 64
	s_cbranch_scc0 .LBB0_503
	s_and_saveexec_b64 s[12:13], s[2:3]
	s_cbranch_execz .LBB0_506
	s_nop 8
	ds_write2st64_b32 v32, v2, v3 offset0:64 offset1:68
	ds_write2st64_b32 v32, v4, v5 offset0:72 offset1:76
	ds_write2st64_b32 v32, v6, v7 offset0:80 offset1:84
	ds_write2st64_b32 v32, v8, v9 offset0:88 offset1:92
	ds_write2st64_b32 v32, v10, v11 offset0:96 offset1:100
	ds_write2st64_b32 v32, v12, v13 offset0:104 offset1:108
	ds_write2st64_b32 v32, v14, v15 offset0:112 offset1:116
	ds_write2st64_b32 v32, v16, v17 offset0:120 offset1:124

; DI bf16_t f2bf(float a) { return (bf16_t)(pk2(a, 0.f) & 0xffffu); }
; DI void phase_cmp(const Params& p, int l, char* smem) {
;     ...
;       for (int q = 0; q < 32; ++q) c1 += ((const float*)(p.ws + OFF_C1))[(lk * 32 + q) * 128 + 32 * w + r];
; #pragma unroll
;       for (int i = 0; i < 16; ++i) {
;         const int m = (i & 3) + 8 * (i >> 2) + 4 * h;
;         hid[m * 136 + 32 * w + r] = f2bf(gelu_tanh(acc[i] + part[i * 256 + tid] + c1));
.LBB0_508:
	v_add_u32_e32 v30, s15, v29
	v_mov_b32_e32 v38, v30
	v_ashrrev_i32_e32 v39, 31, v38
	v_lshl_add_u64 v[38:39], v[38:39], 2, s[20:21]
	global_load_dword v60, v[38:39], off
	v_add_u32_e32 v38, 0x80, v30
	v_ashrrev_i32_e32 v39, 31, v38
	v_lshl_add_u64 v[38:39], v[38:39], 2, s[20:21]
	global_load_dword v61, v[38:39], off
	v_add_u32_e32 v38, 0x100, v30
	v_ashrrev_i32_e32 v39, 31, v38
	v_lshl_add_u64 v[38:39], v[38:39], 2, s[20:21]
	global_load_dword v62, v[38:39], off
	v_add_u32_e32 v38, 0x180, v30
	v_ashrrev_i32_e32 v39, 31, v38
	v_lshl_add_u64 v[38:39], v[38:39], 2, s[20:21]
	global_load_dword v63, v[38:39], off
	v_add_u32_e32 v38, 0x200, v30
	v_ashrrev_i32_e32 v39, 31, v38
	v_lshl_add_u64 v[38:39], v[38:39], 2, s[20:21]
	global_load_dword v64, v[38:39], off
	v_add_u32_e32 v38, 0x280, v30
	v_ashrrev_i32_e32 v39, 31, v38
	v_lshl_add_u64 v[38:39], v[38:39], 2, s[20:21]
	global_load_dword v65, v[38:39], off
	v_add_u32_e32 v38, 0x300, v30
	v_ashrrev_i32_e32 v39, 31, v38
	v_lshl_add_u64 v[38:39], v[38:39], 2, s[20:21]
	global_load_dword v66, v[38:39], off
	v_add_u32_e32 v38, 0x380, v30
	v_ashrrev_i32_e32 v39, 31, v38
	v_lshl_add_u64 v[38:39], v[38:39], 2, s[20:21]
	global_load_dword v67, v[38:39], off
	s_addk_i32 s15, 0x400
	s_waitcnt vmcnt(7)
	v_add_f32_e32 v28, v28, v60
	s_waitcnt vmcnt(6)
	v_add_f32_e32 v28, v28, v61
	s_waitcnt vmcnt(5)
	v_add_f32_e32 v28, v28, v62
	s_waitcnt vmcnt(4)
	v_add_f32_e32 v28, v28, v63
	s_waitcnt vmcnt(3)
	v_add_f32_e32 v28, v28, v64
	s_waitcnt vmcnt(2)
	v_add_f32_e32 v28, v28, v65
	s_waitcnt vmcnt(1)
	v_add_f32_e32 v28, v28, v66
	s_waitcnt vmcnt(0)
	v_add_f32_e32 v28, v28, v67
	s_cmpk_eq_i32 s15, 0x1000
	s_cbranch_scc0 .LBB0_508
	ds_read2st64_b32 v[30:31], v33 offset0:64 offset1:68
	s_waitcnt lgkmcnt(0)
	v_add_f32_e32 v2, v2, v30
	v_add_f32_e32 v3, v3, v31
	v_add_f32_e32 v2, v28, v2
	v_add_f32_e32 v29, v28, v3
	v_mul_f32_e32 v3, 0x3d372713, v2
	v_mul_f32_e32 v3, v2, v3
	v_fma_f32 v3, v2, v3, v2
	v_mul_f32_e32 v3, 0x3f4c422a, v3
	v_add_f32_e32 v3, v3, v3
	v_mul_f32_e32 v3, 0x3fb8aa3b, v3
	v_exp_f32_e32 v3, v3
	v_mul_f32_e32 v30, 0x3d372713, v29
	v_mul_f32_e32 v30, v29, v30
	v_fma_f32 v30, v29, v30, v29
	v_add_f32_e32 v3, 1.0, v3
	v_div_scale_f32 v31, s[20:21], v3, v3, 2.0
	v_rcp_f32_e32 v37, v31
	v_mul_f32_e32 v30, 0x3f4c422a, v30
	v_add_f32_e32 v30, v30, v30
	v_div_scale_f32 v38, vcc, 2.0, v3, 2.0
	v_fma_f32 v39, -v31, v37, 1.0
	v_fmac_f32_e32 v37, v39, v37
	v_mul_f32_e32 v30, 0x3fb8aa3b, v30
	v_mul_f32_e32 v39, v38, v37
	v_exp_f32_e32 v30, v30
	v_fma_f32 v40, -v31, v39, v38
	v_fmac_f32_e32 v39, v40, v37
	v_fma_f32 v31, -v31, v39, v38
	v_div_fmas_f32 v31, v31, v37, v39
	v_add_f32_e32 v30, 1.0, v30
	v_div_fixup_f32 v3, v31, v3, 2.0
	v_div_scale_f32 v31, s[20:21], v30, v30, 2.0
	v_sub_f32_e32 v3, 1.0, v3
	v_rcp_f32_e32 v37, v31
	v_mul_f32_e32 v2, 0.5, v2
	v_add_f32_e32 v3, 1.0, v3
	v_mul_f32_e32 v2, v2, v3
	v_cvt_pk_bf16_f32 v2, v2, s0
	ds_write_b16 v36, v2
	v_fma_f32 v2, -v31, v37, 1.0
	v_fmac_f32_e32 v37, v2, v37
	v_div_scale_f32 v38, vcc, 2.0, v30, 2.0
	v_mul_f32_e32 v39, v38, v37
	v_fma_f32 v2, -v31, v39, v38
	v_fmac_f32_e32 v39, v2, v37
	ds_read2st64_b32 v[2:3], v33 offset0:72 offset1:76
	v_fma_f32 v31, -v31, v39, v38
	v_div_fmas_f32 v31, v31, v37, v39
	v_div_fixup_f32 v30, v31, v30, 2.0
	v_sub_f32_e32 v30, 1.0, v30
	s_waitcnt lgkmcnt(0)
	v_add_f32_e32 v2, v4, v2
	v_add_f32_e32 v2, v28, v2
	v_mul_f32_e32 v4, 0x3d372713, v2
	v_mul_f32_e32 v4, v2, v4
	v_fma_f32 v4, v2, v4, v2
	v_mul_f32_e32 v4, 0x3f4c422a, v4
	v_add_f32_e32 v4, v4, v4
	v_mul_f32_e32 v4, 0x3fb8aa3b, v4
	v_exp_f32_e32 v4, v4
	v_add_f32_e32 v3, v5, v3
	v_add_f32_e32 v5, v28, v3
	v_mul_f32_e32 v29, 0.5, v29
	v_add_f32_e32 v4, 1.0, v4
	v_div_scale_f32 v31, s[20:21], v4, v4, 2.0
	v_rcp_f32_e32 v37, v31
	v_add_f32_e32 v30, 1.0, v30
	v_mul_f32_e32 v3, 0x3d372713, v5
	v_mul_f32_e32 v29, v29, v30
	v_mul_f32_e32 v3, v5, v3
	v_cvt_pk_bf16_f32 v29, v29, s0
	v_fma_f32 v3, v5, v3, v5
	ds_write_b16 v36, v29 offset:272
	v_fma_f32 v29, -v31, v37, 1.0
	v_mul_f32_e32 v3, 0x3f4c422a, v3
	v_fmac_f32_e32 v37, v29, v37
	v_div_scale_f32 v29, vcc, 2.0, v4, 2.0
	v_add_f32_e32 v3, v3, v3
	v_mul_f32_e32 v30, v29, v37
	v_mul_f32_e32 v3, 0x3fb8aa3b, v3
	v_fma_f32 v38, -v31, v30, v29
	v_exp_f32_e32 v3, v3
	v_fmac_f32_e32 v30, v38, v37
	v_fma_f32 v29, -v31, v30, v29
	v_div_fmas_f32 v29, v29, v37, v30
	v_div_fixup_f32 v4, v29, v4, 2.0
	v_add_f32_e32 v29, 1.0, v3
	v_div_scale_f32 v30, s[20:21], v29, v29, 2.0
	v_sub_f32_e32 v4, 1.0, v4
	v_rcp_f32_e32 v31, v30
	v_mul_f32_e32 v2, 0.5, v2
	v_add_f32_e32 v4, 1.0, v4
	v_mul_f32_e32 v2, v2, v4
	v_cvt_pk_bf16_f32 v2, v2, s0
	ds_write_b16 v36, v2 offset:544
	v_fma_f32 v2, -v30, v31, 1.0
	v_fmac_f32_e32 v31, v2, v31
	v_div_scale_f32 v4, vcc, 2.0, v29, 2.0
	v_mul_f32_e32 v37, v4, v31
	v_fma_f32 v2, -v30, v37, v4
	v_fmac_f32_e32 v37, v2, v31
	ds_read2st64_b32 v[2:3], v33 offset0:80 offset1:84
	v_fma_f32 v4, -v30, v37, v4
	v_div_fmas_f32 v4, v4, v31, v37
	v_div_fixup_f32 v4, v4, v29, 2.0
	v_sub_f32_e32 v4, 1.0, v4
	s_waitcnt lgkmcnt(0)
; DI bf16_t f2bf(float a) { return (bf16_t)(pk2(a, 0.f) & 0xffffu); }
; DI float gelu_tanh(float x) {
;   const float u = 0.7978845608028654f * (x + 0.044715f * x * x * x);
;   const float e = __expf(2.f * u);
;   const float t = 1.f - 2.f / (e + 1.f);
;   return 0.5f * x * (1.f + t);
; }
; DI void phase_cmp(const Params& p, int l, char* smem) {
;     ...
;       for (int i = 0; i < 16; ++i) {
;         const int m = (i & 3) + 8 * (i >> 2) + 4 * h;
;         hid[m * 136 + 32 * w + r] = f2bf(gelu_tanh(acc[i] + part[i * 256 + tid] + c1));
;       }
	v_add_f32_e32 v2, v6, v2
	v_add_f32_e32 v2, v28, v2
	v_mul_f32_e32 v6, 0x3d372713, v2
	v_mul_f32_e32 v6, v2, v6
	v_fma_f32 v6, v2, v6, v2
	v_mul_f32_e32 v6, 0x3f4c422a, v6
	v_add_f32_e32 v6, v6, v6
	v_mul_f32_e32 v6, 0x3fb8aa3b, v6
	v_exp_f32_e32 v6, v6
	v_mul_f32_e32 v5, 0.5, v5
	v_add_f32_e32 v4, 1.0, v4
	v_mul_f32_e32 v4, v5, v4
	v_add_f32_e32 v6, 1.0, v6
	v_div_scale_f32 v29, s[20:21], v6, v6, 2.0
	v_rcp_f32_e32 v30, v29
	v_cvt_pk_bf16_f32 v4, v4, s0
	ds_write_b16 v36, v4 offset:816
	v_add_f32_e32 v3, v7, v3
	v_fma_f32 v4, -v29, v30, 1.0
	v_fmac_f32_e32 v30, v4, v30
	v_div_scale_f32 v4, vcc, 2.0, v6, 2.0
	v_mul_f32_e32 v5, v4, v30
	v_fma_f32 v31, -v29, v5, v4
	v_fmac_f32_e32 v5, v31, v30
	v_fma_f32 v4, -v29, v5, v4
	v_div_fmas_f32 v4, v4, v30, v5
	v_add_f32_e32 v5, v28, v3
	v_mul_f32_e32 v3, 0x3d372713, v5
	v_mul_f32_e32 v3, v5, v3
	v_fma_f32 v3, v5, v3, v5
	v_mul_f32_e32 v3, 0x3f4c422a, v3
	v_add_f32_e32 v3, v3, v3
	v_mul_f32_e32 v3, 0x3fb8aa3b, v3
	v_exp_f32_e32 v3, v3
	v_div_fixup_f32 v4, v4, v6, 2.0
	v_sub_f32_e32 v4, 1.0, v4
	v_mul_f32_e32 v2, 0.5, v2
	v_add_f32_e32 v6, 1.0, v3
	v_div_scale_f32 v7, s[20:21], v6, v6, 2.0
	v_rcp_f32_e32 v29, v7
	v_add_f32_e32 v4, 1.0, v4
	v_mul_f32_e32 v2, v2, v4
	v_cvt_pk_bf16_f32 v2, v2, s0
	ds_write_b16 v36, v2 offset:2176
	v_fma_f32 v2, -v7, v29, 1.0
	v_fmac_f32_e32 v29, v2, v29
	v_div_scale_f32 v4, vcc, 2.0, v6, 2.0
	v_mul_f32_e32 v30, v4, v29
	v_fma_f32 v2, -v7, v30, v4
	v_fmac_f32_e32 v30, v2, v29
	ds_read2st64_b32 v[2:3], v33 offset0:88 offset1:92
	v_fma_f32 v4, -v7, v30, v4
	v_div_fmas_f32 v4, v4, v29, v30
	v_div_fixup_f32 v4, v4, v6, 2.0
	v_sub_f32_e32 v4, 1.0, v4
	s_waitcnt lgkmcnt(0)
	v_add_f32_e32 v2, v8, v2
	v_add_f32_e32 v2, v28, v2
	v_mul_f32_e32 v6, 0x3d372713, v2
	v_mul_f32_e32 v6, v2, v6
	v_fma_f32 v6, v2, v6, v2
	v_mul_f32_e32 v6, 0x3f4c422a, v6
	v_add_f32_e32 v6, v6, v6
	v_mul_f32_e32 v6, 0x3fb8aa3b, v6
	v_exp_f32_e32 v6, v6
	v_mul_f32_e32 v5, 0.5, v5
	v_add_f32_e32 v4, 1.0, v4
	v_mul_f32_e32 v4, v5, v4
	v_add_f32_e32 v6, 1.0, v6
	v_div_scale_f32 v7, s[20:21], v6, v6, 2.0
	v_rcp_f32_e32 v8, v7
	v_cvt_pk_bf16_f32 v4, v4, s0
	ds_write_b16 v36, v4 offset:2448
	v_add_f32_e32 v3, v9, v3
	v_fma_f32 v4, -v7, v8, 1.0
	v_fmac_f32_e32 v8, v4, v8
	v_div_scale_f32 v4, vcc, 2.0, v6, 2.0
	v_mul_f32_e32 v5, v4, v8
	v_fma_f32 v29, -v7, v5, v4
	v_fmac_f32_e32 v5, v29, v8
	v_fma_f32 v4, -v7, v5, v4
	v_div_fmas_f32 v4, v4, v8, v5
	v_add_f32_e32 v5, v28, v3
	v_mul_f32_e32 v3, 0x3d372713, v5
	v_mul_f32_e32 v3, v5, v3
	v_fma_f32 v3, v5, v3, v5
	v_mul_f32_e32 v3, 0x3f4c422a, v3
	v_add_f32_e32 v3, v3, v3
	v_mul_f32_e32 v3, 0x3fb8aa3b, v3
	v_exp_f32_e32 v3, v3
	v_div_fixup_f32 v4, v4, v6, 2.0
	v_sub_f32_e32 v4, 1.0, v4
	v_mul_f32_e32 v2, 0.5, v2
	v_add_f32_e32 v6, 1.0, v3
	v_div_scale_f32 v7, s[20:21], v6, v6, 2.0
	v_rcp_f32_e32 v8, v7
	v_add_f32_e32 v4, 1.0, v4
	v_mul_f32_e32 v2, v2, v4
	v_cvt_pk_bf16_f32 v2, v2, s0
	ds_write_b16 v36, v2 offset:2720
	v_fma_f32 v2, -v7, v8, 1.0
	v_fmac_f32_e32 v8, v2, v8
	v_div_scale_f32 v4, vcc, 2.0, v6, 2.0
	v_mul_f32_e32 v9, v4, v8
	v_fma_f32 v2, -v7, v9, v4
	v_fmac_f32_e32 v9, v2, v8
	ds_read2st64_b32 v[2:3], v33 offset0:96 offset1:100
	v_fma_f32 v4, -v7, v9, v4
	v_div_fmas_f32 v4, v4, v8, v9
	v_div_fixup_f32 v4, v4, v6, 2.0
	v_sub_f32_e32 v4, 1.0, v4
	s_waitcnt lgkmcnt(0)
	v_add_f32_e32 v2, v10, v2
	v_add_f32_e32 v2, v28, v2
	v_mul_f32_e32 v6, 0x3d372713, v2
	v_mul_f32_e32 v6, v2, v6
	v_fma_f32 v6, v2, v6, v2
	v_mul_f32_e32 v6, 0x3f4c422a, v6
	v_add_f32_e32 v6, v6, v6
	v_mul_f32_e32 v6, 0x3fb8aa3b, v6
	v_exp_f32_e32 v6, v6
	v_mul_f32_e32 v5, 0.5, v5
	v_add_f32_e32 v4, 1.0, v4
	v_mul_f32_e32 v4, v5, v4
	v_add_f32_e32 v6, 1.0, v6
	v_div_scale_f32 v7, s[20:21], v6, v6, 2.0
	v_rcp_f32_e32 v8, v7
	v_cvt_pk_bf16_f32 v4, v4, s0
	ds_write_b16 v36, v4 offset:2992
	v_add_f32_e32 v3, v11, v3
	v_fma_f32 v4, -v7, v8, 1.0
	v_fmac_f32_e32 v8, v4, v8
	v_div_scale_f32 v4, vcc, 2.0, v6, 2.0
	v_mul_f32_e32 v5, v4, v8
	v_fma_f32 v9, -v7, v5, v4
	v_fmac_f32_e32 v5, v9, v8
	v_fma_f32 v4, -v7, v5, v4
	v_div_fmas_f32 v4, v4, v8, v5
	v_add_f32_e32 v5, v28, v3
	v_mul_f32_e32 v3, 0x3d372713, v5
	v_mul_f32_e32 v3, v5, v3
	v_fma_f32 v3, v5, v3, v5
	v_mul_f32_e32 v3, 0x3f4c422a, v3
	v_add_f32_e32 v3, v3, v3
	v_mul_f32_e32 v3, 0x3fb8aa3b, v3
	v_exp_f32_e32 v3, v3
	v_div_fixup_f32 v4, v4, v6, 2.0
	v_sub_f32_e32 v4, 1.0, v4
	v_mul_f32_e32 v2, 0.5, v2
	v_add_f32_e32 v6, 1.0, v3
	v_div_scale_f32 v7, s[20:21], v6, v6, 2.0
	v_rcp_f32_e32 v8, v7
	v_add_f32_e32 v4, 1.0, v4
	v_mul_f32_e32 v2, v2, v4
	v_cvt_pk_bf16_f32 v2, v2, s0
	ds_write_b16 v36, v2 offset:4352
	v_fma_f32 v2, -v7, v8, 1.0
	v_fmac_f32_e32 v8, v2, v8
	v_div_scale_f32 v4, vcc, 2.0, v6, 2.0
	v_mul_f32_e32 v9, v4, v8
	v_fma_f32 v2, -v7, v9, v4
	v_fmac_f32_e32 v9, v2, v8
	ds_read2st64_b32 v[2:3], v33 offset0:104 offset1:108
	v_fma_f32 v4, -v7, v9, v4
	v_div_fmas_f32 v4, v4, v8, v9
	v_div_fixup_f32 v4, v4, v6, 2.0
	v_sub_f32_e32 v4, 1.0, v4
	s_waitcnt lgkmcnt(0)
; DI bf16_t f2bf(float a) { return (bf16_t)(pk2(a, 0.f) & 0xffffu); }
; DI float gelu_tanh(float x) {
;   const float u = 0.7978845608028654f * (x + 0.044715f * x * x * x);
;   const float e = __expf(2.f * u);
;   const float t = 1.f - 2.f / (e + 1.f);
;   return 0.5f * x * (1.f + t);
; }
; DI void phase_cmp(const Params& p, int l, char* smem) {
;     ...
;       for (int i = 0; i < 16; ++i) {
;         const int m = (i & 3) + 8 * (i >> 2) + 4 * h;
;         hid[m * 136 + 32 * w + r] = f2bf(gelu_tanh(acc[i] + part[i * 256 + tid] + c1));
;       }
	v_add_f32_e32 v2, v12, v2
	v_add_f32_e32 v2, v28, v2
	v_mul_f32_e32 v6, 0x3d372713, v2
	v_mul_f32_e32 v6, v2, v6
	v_fma_f32 v6, v2, v6, v2
	v_mul_f32_e32 v6, 0x3f4c422a, v6
	v_add_f32_e32 v6, v6, v6
	v_mul_f32_e32 v6, 0x3fb8aa3b, v6
	v_exp_f32_e32 v6, v6
	v_mul_f32_e32 v5, 0.5, v5
	v_add_f32_e32 v4, 1.0, v4
	v_mul_f32_e32 v4, v5, v4
	v_add_f32_e32 v6, 1.0, v6
	v_div_scale_f32 v7, s[20:21], v6, v6, 2.0
	v_rcp_f32_e32 v8, v7
	v_cvt_pk_bf16_f32 v4, v4, s0
	ds_write_b16 v36, v4 offset:4624
	v_add_f32_e32 v3, v13, v3
	v_fma_f32 v4, -v7, v8, 1.0
	v_fmac_f32_e32 v8, v4, v8
	v_div_scale_f32 v4, vcc, 2.0, v6, 2.0
	v_mul_f32_e32 v5, v4, v8
	v_fma_f32 v9, -v7, v5, v4
	v_fmac_f32_e32 v5, v9, v8
	v_fma_f32 v4, -v7, v5, v4
	v_div_fmas_f32 v4, v4, v8, v5
	v_add_f32_e32 v5, v28, v3
	v_mul_f32_e32 v3, 0x3d372713, v5
	v_mul_f32_e32 v3, v5, v3
	v_fma_f32 v3, v5, v3, v5
	v_mul_f32_e32 v3, 0x3f4c422a, v3
	v_add_f32_e32 v3, v3, v3
	v_mul_f32_e32 v3, 0x3fb8aa3b, v3
	v_exp_f32_e32 v3, v3
	v_div_fixup_f32 v4, v4, v6, 2.0
	v_sub_f32_e32 v4, 1.0, v4
	v_mul_f32_e32 v2, 0.5, v2
	v_add_f32_e32 v6, 1.0, v3
	v_div_scale_f32 v7, s[20:21], v6, v6, 2.0
	v_rcp_f32_e32 v8, v7
	v_add_f32_e32 v4, 1.0, v4
	v_mul_f32_e32 v2, v2, v4
	v_cvt_pk_bf16_f32 v2, v2, s0
	ds_write_b16 v36, v2 offset:4896
	v_fma_f32 v2, -v7, v8, 1.0
	v_fmac_f32_e32 v8, v2, v8
	v_div_scale_f32 v4, vcc, 2.0, v6, 2.0
	v_mul_f32_e32 v9, v4, v8
	v_fma_f32 v2, -v7, v9, v4
	v_fmac_f32_e32 v9, v2, v8
	ds_read2st64_b32 v[2:3], v33 offset0:112 offset1:116
	v_fma_f32 v4, -v7, v9, v4
	v_div_fmas_f32 v4, v4, v8, v9
	v_div_fixup_f32 v4, v4, v6, 2.0
	v_sub_f32_e32 v4, 1.0, v4
	s_waitcnt lgkmcnt(0)
	v_add_f32_e32 v2, v14, v2
	v_add_f32_e32 v2, v28, v2
	v_mul_f32_e32 v6, 0x3d372713, v2
	v_mul_f32_e32 v6, v2, v6
	v_fma_f32 v6, v2, v6, v2
	v_mul_f32_e32 v6, 0x3f4c422a, v6
	v_add_f32_e32 v6, v6, v6
	v_mul_f32_e32 v6, 0x3fb8aa3b, v6
	v_exp_f32_e32 v6, v6
	v_mul_f32_e32 v5, 0.5, v5
	v_add_f32_e32 v4, 1.0, v4
	v_mul_f32_e32 v4, v5, v4
	v_add_f32_e32 v6, 1.0, v6
	v_div_scale_f32 v7, s[20:21], v6, v6, 2.0
	v_rcp_f32_e32 v8, v7
	v_cvt_pk_bf16_f32 v4, v4, s0
	ds_write_b16 v36, v4 offset:5168
	v_add_f32_e32 v3, v15, v3
	v_fma_f32 v4, -v7, v8, 1.0
	v_fmac_f32_e32 v8, v4, v8
	v_div_scale_f32 v4, vcc, 2.0, v6, 2.0
	v_mul_f32_e32 v5, v4, v8
	v_fma_f32 v9, -v7, v5, v4
	v_fmac_f32_e32 v5, v9, v8
	v_fma_f32 v4, -v7, v5, v4
	v_div_fmas_f32 v4, v4, v8, v5
	v_add_f32_e32 v5, v28, v3
	v_mul_f32_e32 v3, 0x3d372713, v5
	v_mul_f32_e32 v3, v5, v3
	v_fma_f32 v3, v5, v3, v5
	v_mul_f32_e32 v3, 0x3f4c422a, v3
	v_add_f32_e32 v3, v3, v3
	v_mul_f32_e32 v3, 0x3fb8aa3b, v3
	v_exp_f32_e32 v3, v3
	v_div_fixup_f32 v4, v4, v6, 2.0
	v_sub_f32_e32 v4, 1.0, v4
	v_mul_f32_e32 v2, 0.5, v2
	v_add_f32_e32 v6, 1.0, v3
	v_div_scale_f32 v7, s[20:21], v6, v6, 2.0
	v_rcp_f32_e32 v8, v7
	v_add_f32_e32 v4, 1.0, v4
	v_mul_f32_e32 v2, v2, v4
	v_cvt_pk_bf16_f32 v2, v2, s0
	ds_write_b16 v36, v2 offset:6528
	v_fma_f32 v2, -v7, v8, 1.0
	v_fmac_f32_e32 v8, v2, v8
	v_div_scale_f32 v4, vcc, 2.0, v6, 2.0
	v_mul_f32_e32 v9, v4, v8
	v_fma_f32 v2, -v7, v9, v4
	v_fmac_f32_e32 v9, v2, v8
	ds_read2st64_b32 v[2:3], v33 offset0:120 offset1:124
	v_fma_f32 v4, -v7, v9, v4
	v_div_fmas_f32 v4, v4, v8, v9
	v_div_fixup_f32 v4, v4, v6, 2.0
	v_sub_f32_e32 v4, 1.0, v4
	s_waitcnt lgkmcnt(0)
	v_add_f32_e32 v2, v16, v2
	v_add_f32_e32 v2, v28, v2
	v_mul_f32_e32 v6, 0x3d372713, v2
	v_mul_f32_e32 v6, v2, v6
	v_fma_f32 v6, v2, v6, v2
	v_mul_f32_e32 v6, 0x3f4c422a, v6
	v_add_f32_e32 v6, v6, v6
	v_mul_f32_e32 v6, 0x3fb8aa3b, v6
	v_exp_f32_e32 v6, v6
	v_mul_f32_e32 v5, 0.5, v5
	v_add_f32_e32 v4, 1.0, v4
	v_mul_f32_e32 v4, v5, v4
	v_add_f32_e32 v6, 1.0, v6
	v_div_scale_f32 v7, s[20:21], v6, v6, 2.0
	v_rcp_f32_e32 v8, v7
	v_cvt_pk_bf16_f32 v4, v4, s0
	ds_write_b16 v36, v4 offset:6800
	v_add_f32_e32 v3, v17, v3
	v_fma_f32 v4, -v7, v8, 1.0
	v_fmac_f32_e32 v8, v4, v8
	v_div_scale_f32 v4, vcc, 2.0, v6, 2.0
	v_mul_f32_e32 v5, v4, v8
	v_fma_f32 v9, -v7, v5, v4
	v_fmac_f32_e32 v5, v9, v8
	v_fma_f32 v4, -v7, v5, v4
	v_add_f32_e32 v3, v28, v3
	v_div_fmas_f32 v4, v4, v8, v5
	v_mul_f32_e32 v5, 0x3d372713, v3
	v_mul_f32_e32 v5, v3, v5
	v_fma_f32 v5, v3, v5, v3
	v_mul_f32_e32 v5, 0x3f4c422a, v5
	v_add_f32_e32 v5, v5, v5
	v_mul_f32_e32 v5, 0x3fb8aa3b, v5
	v_exp_f32_e32 v5, v5
	v_div_fixup_f32 v4, v4, v6, 2.0
	v_sub_f32_e32 v4, 1.0, v4
	v_mul_f32_e32 v2, 0.5, v2
	v_add_f32_e32 v5, 1.0, v5
	v_div_scale_f32 v6, s[20:21], v5, v5, 2.0
	v_rcp_f32_e32 v7, v6
	v_add_f32_e32 v4, 1.0, v4
	v_mul_f32_e32 v2, v2, v4
	v_cvt_pk_bf16_f32 v2, v2, s0
	ds_write_b16 v36, v2 offset:7072
	v_fma_f32 v2, -v6, v7, 1.0
	v_fmac_f32_e32 v7, v2, v7
	v_div_scale_f32 v2, vcc, 2.0, v5, 2.0
	v_mul_f32_e32 v4, v2, v7
	v_fma_f32 v8, -v6, v4, v2
	v_fmac_f32_e32 v4, v8, v7
	v_fma_f32 v2, -v6, v4, v2
	v_div_fmas_f32 v2, v2, v7, v4
	v_div_fixup_f32 v2, v2, v5, 2.0
	v_sub_f32_e32 v2, 1.0, v2
	v_mul_f32_e32 v3, 0.5, v3
	v_add_f32_e32 v2, 1.0, v2
	v_mul_f32_e32 v2, v3, v2
	v_cvt_pk_bf16_f32 v2, v2, s0
	ds_write_b16 v36, v2 offset:7344
